# attention: stagger scaffolding removed completely from the four compute-segment heads (compiler's original one-branch head restored); on v092
# baseline (speedup 1.0000x reference)
.LBB0_447:
	s_lshl_b32 s59, s57, 7
	s_cmp_lt_u32 s57, 2
	s_waitcnt vmcnt(3)
	ds_write_b128 v200, v[80:83]
	s_waitcnt vmcnt(2)
	ds_write_b128 v200, v[84:87] offset:18432
	s_waitcnt vmcnt(1)
	ds_write_b128 v201, v[88:91]
	s_waitcnt vmcnt(0)
	ds_write_b128 v201, v[92:95] offset:18432
	s_waitcnt lgkmcnt(0)
	s_barrier
	s_cbranch_scc1 .LBB0_449
	s_add_i32 s0, s59, 0xffffff00
	v_add_u32_e32 v32, s0, v198
	v_ashrrev_i32_e32 v33, 31, v32
	v_lshlrev_b64 v[32:33], 7, v[32:33]
	v_lshl_add_u64 v[34:35], v[166:167], 0, v[32:33]
	v_lshl_add_u64 v[32:33], v[168:169], 0, v[32:33]
	global_load_dwordx4 v[80:83], v[34:35], off
	global_load_dwordx4 v[84:87], v[32:33], off
	v_add_u32_e32 v32, s0, v199
	v_ashrrev_i32_e32 v33, 31, v32
	v_lshlrev_b64 v[32:33], 7, v[32:33]
	v_lshl_add_u64 v[34:35], v[170:171], 0, v[32:33]
	v_lshl_add_u64 v[32:33], v[172:173], 0, v[32:33]
	global_load_dwordx4 v[88:91], v[34:35], off
	global_load_dwordx4 v[92:95], v[32:33], off

.LBB0_484:
	s_cmp_lt_u32 s57, 3
	s_waitcnt vmcnt(3)
	ds_write_b128 v200, v[96:99] offset:45056
	s_waitcnt vmcnt(2)
	ds_write_b128 v200, v[100:103] offset:63488
	s_waitcnt vmcnt(1)
	ds_write_b128 v201, v[104:107] offset:45056
	s_waitcnt vmcnt(0)
	ds_write_b128 v201, v[108:111] offset:63488
	s_waitcnt lgkmcnt(0)
	s_barrier
	s_cbranch_scc1 .LBB0_486
	s_add_i32 s0, s59, 0xfffffe80
	v_add_u32_e32 v32, s0, v198
	v_ashrrev_i32_e32 v33, 31, v32
	v_lshlrev_b64 v[32:33], 7, v[32:33]
	v_lshl_add_u64 v[34:35], v[166:167], 0, v[32:33]
	v_lshl_add_u64 v[32:33], v[168:169], 0, v[32:33]
	global_load_dwordx4 v[96:99], v[34:35], off
	global_load_dwordx4 v[100:103], v[32:33], off
	v_add_u32_e32 v32, s0, v199
	v_ashrrev_i32_e32 v33, 31, v32
	v_lshlrev_b64 v[32:33], 7, v[32:33]
	v_lshl_add_u64 v[34:35], v[170:171], 0, v[32:33]
	v_lshl_add_u64 v[32:33], v[172:173], 0, v[32:33]
	global_load_dwordx4 v[104:107], v[34:35], off
	global_load_dwordx4 v[108:111], v[32:33], off
